# attention queue: three (instead of two) heaviest 256-query tiles run as 128-query half units, on the full stack
# baseline (speedup 1.0000x reference)
; __global__ void __launch_bounds__(512, 2) mega(Params p) {
;     ...
;                 QUEUE_BEGIN(512 + 256)
;                     if (item >= 256 && item < 512) {
;                         bf16_t* P = (bf16_t*)(R1 + R_P);
;                         const int qt = 15 - ((item - 256) >> 4), bl = (item >> 3) & 1, h = item & 7;
;                         AttnArgs a; a.Q = P + C_SBQ + h * 64; a.ldq = NINP; a.K = P + C_SBK + h * 64; a.ldk = NINP; a.K2 = nullptr; a.ldk2 = 0;
;                         a.V = P + C_SBV + h * 64; a.ldv = NINP; a.O = (bf16_t*)(R1 + R_OA) + h * 64; a.ldo = 512; a.lse = nullptr; a.ldl = 0;
;                         a.q0 = qt * 256; a.tstride = 1; a.toff = bl * SEQ; a.nk = 0; a.c2 = 0.125f * LOG2E; a.biasg = nullptr;
;                         attn_unit<2>(lds, a);
;                     } else if (item < 256) {
;                         const int qt = 15 - (item >> 4), bl = (item >> 3) & 1, h = item & 7;
;                         bf16_t* kvm = (bf16_t*)(R1 + R_KVM);
;                         AttnArgs a; a.Q = (bf16_t*)(R1 + R_QM) + h * 96; a.ldq = 768; a.K = kvm + h * 128; a.ldk = 1024; a.K2 = (bf16_t*)(R1 + R_P) + C_KR; a.ldk2 = NINP;
;                         a.V = kvm + h * 128 + 64; a.ldv = 1024; a.O = (bf16_t*)(R1 + R_OA) + (size_t)TC * 512 + h * 64; a.ldo = 512; a.lse = nullptr; a.ldl = 0;
;                         a.q0 = qt * 256; a.tstride = 1; a.toff = bl * SEQ; a.nk = 0; a.c2 = 0.10206207261596577f * LOG2E; a.biasg = nullptr;
;                         attn_unit<1>(lds, a);
;                     } else {
;                         const int t0 = (item - 512) * 32;
;                         bf16_t* oc = (bf16_t*)(R1 + R_OA) + (size_t)2 * TC * 512;
;                         const bf16_t* og = (const bf16_t*)(R1 + R_OG);
;                         const float* lse = (const float*)(R1 + R_LSE);
; #pragma unroll
;                         for (int ps = 0; ps < 4; ++ps) {
;                             const int tok = t0 + ps * 8 + (tid >> 6), c8 = (tid & 63) * 8, h = c8 >> 6;
;                             const float l0 = lse[(size_t)tok * 8 + h], l1 = lse[(size_t)(TC + tok) * 8 + h], l2 = lse[(size_t)(2 * TC + tok) * 8 + h];
;                             const float mx = fmaxf(l0, fmaxf(l1, l2));
;                             float w0 = ex2(l0 - mx), w1 = ex2(l1 - mx), w2 = ex2(l2 - mx);
.LBB0_118:
	s_or_b64 exec, exec, s[6:7]
	s_mov_b32 s0, 0x20000
	s_addk_i32 s0, 0x100
	v_mov_b32_e32 v0, s0
	s_waitcnt lgkmcnt(0)
	s_barrier
	ds_read_b32 v0, v0
	v_readlane_b32 s1, v255, 1
	s_cmp_eq_u32 s1, 0x100
	s_cselect_b32 s1, 0x100, 0
	s_movk_i32 s0, 0x32f
	s_sub_i32 s0, s0, s1
	s_mov_b64 s[6:7], -1
	s_waitcnt lgkmcnt(0)
	v_cmp_lt_i32_e32 vcc, s0, v0
	v_readfirstlane_b32 s18, v0
	s_cbranch_vccnz .LBB0_113
	s_add_i32 s18, s18, s1
.Lq_have:
	s_cmpk_lt_i32 s18, 0x130
	s_cbranch_scc1 .LBB0_122
	s_addk_i32 s18, 0xffd0
	s_and_b32 s0, s18, 0xffffff00
	s_cmpk_lg_i32 s0, 0x100
	s_cbranch_scc0 .LBB0_188
	s_cmpk_gt_i32 s18, 0xff
	s_cbranch_scc0 .LBB0_122
	s_lshl_b32 s0, s18, 5
	v_add_u32_e32 v2, s0, v197
	v_ashrrev_i32_e32 v3, 31, v2
	v_lshlrev_b64 v[4:5], 5, v[2:3]
	v_lshl_add_u64 v[4:5], v[136:137], 0, v[4:5]
	v_lshlrev_b64 v[6:7], 10, v[2:3]
	v_lshl_add_u64 v[8:9], v[138:139], 0, v[6:7]
	v_lshl_add_u64 v[10:11], v[140:141], 0, v[6:7]
	s_mov_b32 s6, 0x40000
	s_mov_b32 s7, 0
	v_lshl_add_u64 v[12:13], v[4:5], 0, s[6:7]
	v_lshl_add_u64 v[14:15], v[12:13], 0, s[6:7]
	s_mov_b32 s6, 0x800000
	v_lshl_add_u64 v[16:17], v[8:9], 0, s[6:7]
	v_lshl_add_u64 v[18:19], v[16:17], 0, s[6:7]
	s_mov_b32 s6, 0x2000
	global_load_dword v30, v[4:5], off
	global_load_dword v31, v[12:13], off
	global_load_dword v32, v[14:15], off
	global_load_dword v33, v[4:5], off offset:256
	global_load_dword v34, v[12:13], off offset:256
	global_load_dword v35, v[14:15], off offset:256
	global_load_dword v36, v[4:5], off offset:512
	global_load_dword v37, v[12:13], off offset:512
	global_load_dword v38, v[14:15], off offset:512
	global_load_dword v39, v[4:5], off offset:768
	global_load_dword v40, v[12:13], off offset:768
	global_load_dword v41, v[14:15], off offset:768
	global_load_dwordx4 v[48:51], v[8:9], off
	global_load_dwordx4 v[52:55], v[16:17], off
	global_load_dwordx4 v[56:59], v[18:19], off
	v_lshl_add_u64 v[8:9], v[8:9], 0, s[6:7]
	v_lshl_add_u64 v[16:17], v[16:17], 0, s[6:7]
	v_lshl_add_u64 v[18:19], v[18:19], 0, s[6:7]
	global_load_dwordx4 v[60:63], v[8:9], off
	global_load_dwordx4 v[64:67], v[16:17], off
	global_load_dwordx4 v[68:71], v[18:19], off
	v_lshl_add_u64 v[8:9], v[8:9], 0, s[6:7]
	v_lshl_add_u64 v[16:17], v[16:17], 0, s[6:7]
	v_lshl_add_u64 v[18:19], v[18:19], 0, s[6:7]
	global_load_dwordx4 v[72:75], v[8:9], off
	global_load_dwordx4 v[76:79], v[16:17], off
	global_load_dwordx4 v[80:83], v[18:19], off
	v_lshl_add_u64 v[8:9], v[8:9], 0, s[6:7]
	v_lshl_add_u64 v[16:17], v[16:17], 0, s[6:7]
	v_lshl_add_u64 v[18:19], v[18:19], 0, s[6:7]
	global_load_dwordx4 v[84:87], v[8:9], off
	global_load_dwordx4 v[88:91], v[16:17], off
	global_load_dwordx4 v[92:95], v[18:19], off
	s_waitcnt vmcnt(12)
	v_max3_f32 v5, v30, v31, v32
	v_sub_f32_e32 v0, v30, v5
	v_exp_f32_e32 v17, v0
	v_sub_f32_e32 v0, v31, v5
	v_exp_f32_e32 v16, v0
	v_sub_f32_e32 v0, v32, v5
	v_exp_f32_e32 v20, v0
	v_add_f32_e32 v0, v17, v16
	v_add_f32_e32 v0, v20, v0
	v_div_scale_f32 v5, s[0:1], v0, v0, 1.0
	v_rcp_f32_e32 v6, v5
	s_nop 0
	v_fma_f32 v7, -v5, v6, 1.0
	v_fmac_f32_e32 v6, v7, v6
	v_div_scale_f32 v7, vcc, 1.0, v0, 1.0
	v_mul_f32_e32 v21, v7, v6
	v_fma_f32 v22, -v5, v21, v7
	v_fmac_f32_e32 v21, v22, v6
	v_fma_f32 v5, -v5, v21, v7
	v_div_fmas_f32 v5, v5, v6, v21
	v_div_fixup_f32 v0, v5, v0, 1.0
	v_mul_f32_e32 v18, v20, v0
	v_pk_mul_f32 v[16:17], v[16:17], v[0:1] op_sel_hi:[1,0]
	s_waitcnt vmcnt(9)
	v_lshlrev_b32_e32 v24, 16, v48
	v_and_b32_e32 v23, 0xffff0000, v48
	v_and_b32_e32 v25, 0xffff0000, v52
	v_lshlrev_b32_e32 v22, 16, v52
	v_lshlrev_b32_e32 v26, 16, v56
	v_and_b32_e32 v27, 0xffff0000, v56
	v_pk_mul_f32 v[24:25], v[16:17], v[24:25] op_sel:[1,0] op_sel_hi:[0,1]
	v_pk_fma_f32 v[22:23], v[16:17], v[22:23], v[24:25]
	v_pk_fma_f32 v[22:23], v[18:19], v[26:27], v[22:23] op_sel_hi:[0,1,1]
	v_cvt_pk_bf16_f32 v100, v22, v23
	v_lshlrev_b32_e32 v24, 16, v49
	v_and_b32_e32 v23, 0xffff0000, v49
	v_and_b32_e32 v25, 0xffff0000, v53
	v_lshlrev_b32_e32 v22, 16, v53
	v_lshlrev_b32_e32 v26, 16, v57
	v_and_b32_e32 v27, 0xffff0000, v57
	v_pk_mul_f32 v[24:25], v[16:17], v[24:25] op_sel:[1,0] op_sel_hi:[0,1]
	v_pk_fma_f32 v[22:23], v[16:17], v[22:23], v[24:25]
	v_pk_fma_f32 v[22:23], v[18:19], v[26:27], v[22:23] op_sel_hi:[0,1,1]
	v_cvt_pk_bf16_f32 v101, v22, v23
	v_lshlrev_b32_e32 v24, 16, v50
	v_and_b32_e32 v23, 0xffff0000, v50
	v_and_b32_e32 v25, 0xffff0000, v54
	v_lshlrev_b32_e32 v22, 16, v54
	v_lshlrev_b32_e32 v26, 16, v58
	v_and_b32_e32 v27, 0xffff0000, v58
	v_pk_mul_f32 v[24:25], v[16:17], v[24:25] op_sel:[1,0] op_sel_hi:[0,1]
	v_pk_fma_f32 v[22:23], v[16:17], v[22:23], v[24:25]
	v_pk_fma_f32 v[22:23], v[18:19], v[26:27], v[22:23] op_sel_hi:[0,1,1]
	v_cvt_pk_bf16_f32 v102, v22, v23
	v_lshlrev_b32_e32 v24, 16, v51
	v_and_b32_e32 v23, 0xffff0000, v51
	v_and_b32_e32 v25, 0xffff0000, v55
	v_lshlrev_b32_e32 v22, 16, v55
	v_lshlrev_b32_e32 v26, 16, v59
	v_and_b32_e32 v27, 0xffff0000, v59
	v_pk_mul_f32 v[24:25], v[16:17], v[24:25] op_sel:[1,0] op_sel_hi:[0,1]
	v_pk_fma_f32 v[22:23], v[16:17], v[22:23], v[24:25]
	v_pk_fma_f32 v[22:23], v[18:19], v[26:27], v[22:23] op_sel_hi:[0,1,1]
	v_cvt_pk_bf16_f32 v103, v22, v23
	global_store_dwordx4 v[10:11], v[100:103], off
	v_max3_f32 v5, v33, v34, v35
	v_sub_f32_e32 v0, v33, v5
	v_exp_f32_e32 v17, v0
	v_sub_f32_e32 v0, v34, v5
	v_exp_f32_e32 v16, v0
	v_sub_f32_e32 v0, v35, v5
	v_exp_f32_e32 v20, v0
	v_add_f32_e32 v0, v17, v16
	v_add_f32_e32 v0, v20, v0
	v_div_scale_f32 v5, s[0:1], v0, v0, 1.0
	v_rcp_f32_e32 v6, v5
	s_nop 0
	v_fma_f32 v7, -v5, v6, 1.0
	v_fmac_f32_e32 v6, v7, v6
	v_div_scale_f32 v7, vcc, 1.0, v0, 1.0
	v_mul_f32_e32 v21, v7, v6
	v_fma_f32 v22, -v5, v21, v7
	v_fmac_f32_e32 v21, v22, v6
	v_fma_f32 v5, -v5, v21, v7
	v_div_fmas_f32 v5, v5, v6, v21
	v_div_fixup_f32 v0, v5, v0, 1.0
	v_mul_f32_e32 v18, v20, v0
	v_pk_mul_f32 v[16:17], v[16:17], v[0:1] op_sel_hi:[1,0]
	s_waitcnt vmcnt(7)
; DI unsigned pk2(float lo, float hi) { f32x2_t v = {lo, hi}; bf16x2_t b = __builtin_convertvector(v, bf16x2_t); return __builtin_bit_cast(unsigned, b); }
; DI float bflo(unsigned u) { return __uint_as_float(u << 16); }
; DI float bfhi(unsigned u) { return __uint_as_float(u & 0xffff0000u); }
; DI float ex2(float x) { return __builtin_amdgcn_exp2f(x); }
; __global__ void __launch_bounds__(512, 2) mega(Params p) {
;     ...
;                         for (int ps = 0; ps < 4; ++ps) {
;                             const int tok = t0 + ps * 8 + (tid >> 6), c8 = (tid & 63) * 8, h = c8 >> 6;
;                             const float l0 = lse[(size_t)tok * 8 + h], l1 = lse[(size_t)(TC + tok) * 8 + h], l2 = lse[(size_t)(2 * TC + tok) * 8 + h];
;                             const float mx = fmaxf(l0, fmaxf(l1, l2));
;                             float w0 = ex2(l0 - mx), w1 = ex2(l1 - mx), w2 = ex2(l2 - mx);
;                             const float is = 1.0f / (w0 + w1 + w2); w0 *= is; w1 *= is; w2 *= is;
;                             const u32x4 a0 = *(const u32x4*)(og + (size_t)tok * 512 + c8), a1 = *(const u32x4*)(og + (size_t)(TC + tok) * 512 + c8), a2 = *(const u32x4*)(og + (size_t)(2 * TC + tok) * 512 + c8);
;                             u32x4 w;
;                             w.x = pk2(w0 * bflo(a0.x) + w1 * bflo(a1.x) + w2 * bflo(a2.x), w0 * bfhi(a0.x) + w1 * bfhi(a1.x) + w2 * bfhi(a2.x));
;                             w.y = pk2(w0 * bflo(a0.y) + w1 * bflo(a1.y) + w2 * bflo(a2.y), w0 * bfhi(a0.y) + w1 * bfhi(a1.y) + w2 * bfhi(a2.y));
;                             w.z = pk2(w0 * bflo(a0.z) + w1 * bflo(a1.z) + w2 * bflo(a2.z), w0 * bfhi(a0.z) + w1 * bfhi(a1.z) + w2 * bfhi(a2.z));
;                             w.w = pk2(w0 * bflo(a0.w) + w1 * bflo(a1.w) + w2 * bflo(a2.w), w0 * bfhi(a0.w) + w1 * bfhi(a1.w) + w2 * bfhi(a2.w));
;                             *(u32x4*)(oc + (size_t)tok * 512 + c8) = w;
;                         }
	v_lshlrev_b32_e32 v24, 16, v60
	v_and_b32_e32 v23, 0xffff0000, v60
	v_and_b32_e32 v25, 0xffff0000, v64
	v_lshlrev_b32_e32 v22, 16, v64
	v_lshlrev_b32_e32 v26, 16, v68
	v_and_b32_e32 v27, 0xffff0000, v68
	v_pk_mul_f32 v[24:25], v[16:17], v[24:25] op_sel:[1,0] op_sel_hi:[0,1]
	v_pk_fma_f32 v[22:23], v[16:17], v[22:23], v[24:25]
	v_pk_fma_f32 v[22:23], v[18:19], v[26:27], v[22:23] op_sel_hi:[0,1,1]
	v_cvt_pk_bf16_f32 v104, v22, v23
	v_lshlrev_b32_e32 v24, 16, v61
	v_and_b32_e32 v23, 0xffff0000, v61
	v_and_b32_e32 v25, 0xffff0000, v65
	v_lshlrev_b32_e32 v22, 16, v65
	v_lshlrev_b32_e32 v26, 16, v69
	v_and_b32_e32 v27, 0xffff0000, v69
	v_pk_mul_f32 v[24:25], v[16:17], v[24:25] op_sel:[1,0] op_sel_hi:[0,1]
	v_pk_fma_f32 v[22:23], v[16:17], v[22:23], v[24:25]
	v_pk_fma_f32 v[22:23], v[18:19], v[26:27], v[22:23] op_sel_hi:[0,1,1]
	v_cvt_pk_bf16_f32 v105, v22, v23
	v_lshlrev_b32_e32 v24, 16, v62
	v_and_b32_e32 v23, 0xffff0000, v62
	v_and_b32_e32 v25, 0xffff0000, v66
	v_lshlrev_b32_e32 v22, 16, v66
	v_lshlrev_b32_e32 v26, 16, v70
	v_and_b32_e32 v27, 0xffff0000, v70
	v_pk_mul_f32 v[24:25], v[16:17], v[24:25] op_sel:[1,0] op_sel_hi:[0,1]
	v_pk_fma_f32 v[22:23], v[16:17], v[22:23], v[24:25]
	v_pk_fma_f32 v[22:23], v[18:19], v[26:27], v[22:23] op_sel_hi:[0,1,1]
	v_cvt_pk_bf16_f32 v106, v22, v23
	v_lshlrev_b32_e32 v24, 16, v63
	v_and_b32_e32 v23, 0xffff0000, v63
	v_and_b32_e32 v25, 0xffff0000, v67
	v_lshlrev_b32_e32 v22, 16, v67
	v_lshlrev_b32_e32 v26, 16, v71
	v_and_b32_e32 v27, 0xffff0000, v71
	v_pk_mul_f32 v[24:25], v[16:17], v[24:25] op_sel:[1,0] op_sel_hi:[0,1]
	v_pk_fma_f32 v[22:23], v[16:17], v[22:23], v[24:25]
	v_pk_fma_f32 v[22:23], v[18:19], v[26:27], v[22:23] op_sel_hi:[0,1,1]
	v_cvt_pk_bf16_f32 v107, v22, v23
	v_lshl_add_u64 v[10:11], v[10:11], 0, s[6:7]
	global_store_dwordx4 v[10:11], v[104:107], off
	v_max3_f32 v5, v36, v37, v38
	v_sub_f32_e32 v0, v36, v5
	v_exp_f32_e32 v17, v0
	v_sub_f32_e32 v0, v37, v5
	v_exp_f32_e32 v16, v0
	v_sub_f32_e32 v0, v38, v5
	v_exp_f32_e32 v20, v0
	v_add_f32_e32 v0, v17, v16
	v_add_f32_e32 v0, v20, v0
	v_div_scale_f32 v5, s[0:1], v0, v0, 1.0
	v_rcp_f32_e32 v6, v5
	s_nop 0
	v_fma_f32 v7, -v5, v6, 1.0
	v_fmac_f32_e32 v6, v7, v6
	v_div_scale_f32 v7, vcc, 1.0, v0, 1.0
	v_mul_f32_e32 v21, v7, v6
	v_fma_f32 v22, -v5, v21, v7
	v_fmac_f32_e32 v21, v22, v6
	v_fma_f32 v5, -v5, v21, v7
	v_div_fmas_f32 v5, v5, v6, v21
	v_div_fixup_f32 v0, v5, v0, 1.0
	v_mul_f32_e32 v18, v20, v0
	v_pk_mul_f32 v[16:17], v[16:17], v[0:1] op_sel_hi:[1,0]
	s_waitcnt vmcnt(5)
	v_lshlrev_b32_e32 v24, 16, v72
	v_and_b32_e32 v23, 0xffff0000, v72
	v_and_b32_e32 v25, 0xffff0000, v76
	v_lshlrev_b32_e32 v22, 16, v76
	v_lshlrev_b32_e32 v26, 16, v80
	v_and_b32_e32 v27, 0xffff0000, v80
	v_pk_mul_f32 v[24:25], v[16:17], v[24:25] op_sel:[1,0] op_sel_hi:[0,1]
	v_pk_fma_f32 v[22:23], v[16:17], v[22:23], v[24:25]
	v_pk_fma_f32 v[22:23], v[18:19], v[26:27], v[22:23] op_sel_hi:[0,1,1]
	v_cvt_pk_bf16_f32 v108, v22, v23
	v_lshlrev_b32_e32 v24, 16, v73
	v_and_b32_e32 v23, 0xffff0000, v73
	v_and_b32_e32 v25, 0xffff0000, v77
	v_lshlrev_b32_e32 v22, 16, v77
	v_lshlrev_b32_e32 v26, 16, v81
	v_and_b32_e32 v27, 0xffff0000, v81
	v_pk_mul_f32 v[24:25], v[16:17], v[24:25] op_sel:[1,0] op_sel_hi:[0,1]
	v_pk_fma_f32 v[22:23], v[16:17], v[22:23], v[24:25]
	v_pk_fma_f32 v[22:23], v[18:19], v[26:27], v[22:23] op_sel_hi:[0,1,1]
	v_cvt_pk_bf16_f32 v109, v22, v23
	v_lshlrev_b32_e32 v24, 16, v74
	v_and_b32_e32 v23, 0xffff0000, v74
	v_and_b32_e32 v25, 0xffff0000, v78
	v_lshlrev_b32_e32 v22, 16, v78
	v_lshlrev_b32_e32 v26, 16, v82
	v_and_b32_e32 v27, 0xffff0000, v82
	v_pk_mul_f32 v[24:25], v[16:17], v[24:25] op_sel:[1,0] op_sel_hi:[0,1]
	v_pk_fma_f32 v[22:23], v[16:17], v[22:23], v[24:25]
	v_pk_fma_f32 v[22:23], v[18:19], v[26:27], v[22:23] op_sel_hi:[0,1,1]
	v_cvt_pk_bf16_f32 v110, v22, v23
	v_lshlrev_b32_e32 v24, 16, v75
	v_and_b32_e32 v23, 0xffff0000, v75
	v_and_b32_e32 v25, 0xffff0000, v79
	v_lshlrev_b32_e32 v22, 16, v79
	v_lshlrev_b32_e32 v26, 16, v83
	v_and_b32_e32 v27, 0xffff0000, v83
	v_pk_mul_f32 v[24:25], v[16:17], v[24:25] op_sel:[1,0] op_sel_hi:[0,1]
	v_pk_fma_f32 v[22:23], v[16:17], v[22:23], v[24:25]
	v_pk_fma_f32 v[22:23], v[18:19], v[26:27], v[22:23] op_sel_hi:[0,1,1]
	v_cvt_pk_bf16_f32 v111, v22, v23
	v_lshl_add_u64 v[10:11], v[10:11], 0, s[6:7]
	global_store_dwordx4 v[10:11], v[108:111], off
	v_max3_f32 v5, v39, v40, v41
	v_sub_f32_e32 v0, v39, v5
	v_exp_f32_e32 v17, v0
	v_sub_f32_e32 v0, v40, v5
	v_exp_f32_e32 v16, v0
	v_sub_f32_e32 v0, v41, v5
	v_exp_f32_e32 v20, v0
	v_add_f32_e32 v0, v17, v16
	v_add_f32_e32 v0, v20, v0
	v_div_scale_f32 v5, s[0:1], v0, v0, 1.0
	v_rcp_f32_e32 v6, v5
	s_nop 0
	v_fma_f32 v7, -v5, v6, 1.0
	v_fmac_f32_e32 v6, v7, v6
	v_div_scale_f32 v7, vcc, 1.0, v0, 1.0
	v_mul_f32_e32 v21, v7, v6
	v_fma_f32 v22, -v5, v21, v7
	v_fmac_f32_e32 v21, v22, v6
	v_fma_f32 v5, -v5, v21, v7
	v_div_fmas_f32 v5, v5, v6, v21
	v_div_fixup_f32 v0, v5, v0, 1.0
	v_mul_f32_e32 v18, v20, v0
	v_pk_mul_f32 v[16:17], v[16:17], v[0:1] op_sel_hi:[1,0]
	s_waitcnt vmcnt(3)
	v_lshlrev_b32_e32 v24, 16, v84
	v_and_b32_e32 v23, 0xffff0000, v84
	v_and_b32_e32 v25, 0xffff0000, v88
	v_lshlrev_b32_e32 v22, 16, v88
	v_lshlrev_b32_e32 v26, 16, v92
	v_and_b32_e32 v27, 0xffff0000, v92
	v_pk_mul_f32 v[24:25], v[16:17], v[24:25] op_sel:[1,0] op_sel_hi:[0,1]
	v_pk_fma_f32 v[22:23], v[16:17], v[22:23], v[24:25]
	v_pk_fma_f32 v[22:23], v[18:19], v[26:27], v[22:23] op_sel_hi:[0,1,1]
	v_cvt_pk_bf16_f32 v112, v22, v23
	v_lshlrev_b32_e32 v24, 16, v85
	v_and_b32_e32 v23, 0xffff0000, v85
	v_and_b32_e32 v25, 0xffff0000, v89
	v_lshlrev_b32_e32 v22, 16, v89
	v_lshlrev_b32_e32 v26, 16, v93
	v_and_b32_e32 v27, 0xffff0000, v93
	v_pk_mul_f32 v[24:25], v[16:17], v[24:25] op_sel:[1,0] op_sel_hi:[0,1]
	v_pk_fma_f32 v[22:23], v[16:17], v[22:23], v[24:25]
	v_pk_fma_f32 v[22:23], v[18:19], v[26:27], v[22:23] op_sel_hi:[0,1,1]
	v_cvt_pk_bf16_f32 v113, v22, v23
	v_lshlrev_b32_e32 v24, 16, v86
	v_and_b32_e32 v23, 0xffff0000, v86
	v_and_b32_e32 v25, 0xffff0000, v90
	v_lshlrev_b32_e32 v22, 16, v90
	v_lshlrev_b32_e32 v26, 16, v94
	v_and_b32_e32 v27, 0xffff0000, v94
	v_pk_mul_f32 v[24:25], v[16:17], v[24:25] op_sel:[1,0] op_sel_hi:[0,1]
	v_pk_fma_f32 v[22:23], v[16:17], v[22:23], v[24:25]
	v_pk_fma_f32 v[22:23], v[18:19], v[26:27], v[22:23] op_sel_hi:[0,1,1]
	v_cvt_pk_bf16_f32 v114, v22, v23
	v_lshlrev_b32_e32 v24, 16, v87
	v_and_b32_e32 v23, 0xffff0000, v87
	v_and_b32_e32 v25, 0xffff0000, v91
	v_lshlrev_b32_e32 v22, 16, v91
	v_lshlrev_b32_e32 v26, 16, v95
	v_and_b32_e32 v27, 0xffff0000, v95
	v_pk_mul_f32 v[24:25], v[16:17], v[24:25] op_sel:[1,0] op_sel_hi:[0,1]
	v_pk_fma_f32 v[22:23], v[16:17], v[22:23], v[24:25]
	v_pk_fma_f32 v[22:23], v[18:19], v[26:27], v[22:23] op_sel_hi:[0,1,1]
	v_cvt_pk_bf16_f32 v115, v22, v23
	v_lshl_add_u64 v[10:11], v[10:11], 0, s[6:7]
	global_store_dwordx4 v[10:11], v[112:115], off
	s_mov_b64 s[6:7], 0
; __global__ void __launch_bounds__(512, 2) mega(Params p) {
;     ...
;                     if (item >= 256 && item < 512) {
;                         bf16_t* P = (bf16_t*)(R1 + R_P);
;                         const int qt = 15 - ((item - 256) >> 4), bl = (item >> 3) & 1, h = item & 7;
;                         AttnArgs a; a.Q = P + C_SBQ + h * 64; a.ldq = NINP; a.K = P + C_SBK + h * 64; a.ldk = NINP; a.K2 = nullptr; a.ldk2 = 0;
;                         a.V = P + C_SBV + h * 64; a.ldv = NINP; a.O = (bf16_t*)(R1 + R_OA) + h * 64; a.ldo = 512; a.lse = nullptr; a.ldl = 0;
;                         a.q0 = qt * 256; a.tstride = 1; a.toff = bl * SEQ; a.nk = 0; a.c2 = 0.125f * LOG2E; a.biasg = nullptr;
;                         attn_unit<2>(lds, a);
;                     } else if (item < 256) {
;                         const int qt = 15 - (item >> 4), bl = (item >> 3) & 1, h = item & 7;
;                         bf16_t* kvm = (bf16_t*)(R1 + R_KVM);
;                         AttnArgs a; a.Q = (bf16_t*)(R1 + R_QM) + h * 96; a.ldq = 768; a.K = kvm + h * 128; a.ldk = 1024; a.K2 = (bf16_t*)(R1 + R_P) + C_KR; a.ldk2 = NINP;
;                         a.V = kvm + h * 128 + 64; a.ldv = 1024; a.O = (bf16_t*)(R1 + R_OA) + (size_t)TC * 512 + h * 64; a.ldo = 512; a.lse = nullptr; a.ldl = 0;
;                         a.q0 = qt * 256; a.tstride = 1; a.toff = bl * SEQ; a.nk = 0; a.c2 = 0.10206207261596577f * LOG2E; a.biasg = nullptr;
;                         attn_unit<1>(lds, a);
.LBB0_122:
	s_andn2_b64 vcc, exec, s[6:7]
	s_cbranch_vccnz .LBB0_187
	v_readlane_b32 s100, v255, 13
	v_readlane_b32 s101, v255, 14
	s_and_b32 s1, s18, 7
	s_mul_i32 s0, s1, 0xc0
	v_readlane_b32 s4, v254, 57
	v_readlane_b32 s5, v254, 58
	s_add_u32 s8, s4, s0
	s_addc_u32 s9, s5, 0
	s_lshl_b32 s0, s1, 8
	v_readlane_b32 s4, v254, 55
	v_readlane_b32 s5, v254, 56
	s_add_u32 s6, s4, s0
	s_addc_u32 s7, s5, 0
	s_lshl_b32 s5, s18, 9
	v_mov_b32_e32 v12, v202
	s_lshl_b32 s0, s18, 3
	s_and_b32 s66, s5, 0x1000
	s_and_b32 s0, s0, 0xffffff80
	s_cmpk_lt_i32 s18, 0x60
	s_cselect_b32 s32, 1, 0
	s_cbranch_scc1 .Lq_half
	s_sub_i32 s0, s18, 0x60
	s_lshl_b32 s0, s0, 4
	s_and_b32 s0, s0, 0xffffff00
	s_addk_i32 s0, 0x380
